# P10 batched epilogue + P9 column tiles in descending order (ACT stays hot in Infinity Cache for P10)
# baseline (speedup 1.0000x reference)
.LBB0_1478:
	s_or_b64 exec, exec, s[8:9]
	v_mov_b32_e32 v9, v216
	s_waitcnt lgkmcnt(0)
	s_barrier
	s_cmpk_gt_i32 s2, 0xaff
	v_readfirstlane_b32 s7, v9
	s_cbranch_scc1 .LBB0_1494
	v_lshlrev_b32_e32 v0, 4, v9
	v_add_u32_e32 v1, 0x2000, v0
	v_ashrrev_i32_e32 v2, 31, v1
	v_lshrrev_b32_e32 v2, 22, v2
	v_add_u32_e32 v2, v1, v2
	v_ashrrev_i32_e32 v8, 10, v2
	v_mul_i32_i24_e32 v2, 0x400, v8
	v_sub_u32_e32 v1, v1, v2
	v_lshrrev_b32_e32 v2, 4, v1
	v_bitop3_b32 v1, v2, v1, 32 bitop3:0x6c
	v_ashrrev_i32_e32 v2, 31, v1
	v_lshrrev_b32_e32 v2, 26, v2
	v_add_u32_e32 v2, v1, v2
	v_lshlrev_b32_e32 v3, 3, v8
	v_ashrrev_i32_e32 v10, 6, v2
	v_and_b32_e32 v3, -16, v3
	v_add_u32_e32 v3, v10, v3
	v_and_b32_e32 v4, 3, v10
	s_mov_b32 s8, 0xfffe0
	v_lshrrev_b32_e32 v5, 2, v3
	v_lshlrev_b32_e32 v6, 1, v3
	v_and_b32_e32 v2, 0xc0, v2
	v_and_or_b32 v4, v3, s8, v4
	v_and_b32_e32 v5, 4, v5
	v_and_b32_e32 v6, 24, v6
	v_sub_u32_e32 v1, v1, v2
	v_mov_b32_e32 v2, 1
	v_or3_b32 v4, v4, v5, v6
	v_lshlrev_b32_e32 v5, 5, v8
	v_ashrrev_i16_sdwa v1, v2, sext(v1) dst_sel:DWORD dst_unused:UNUSED_PAD src0_sel:DWORD src1_sel:BYTE_0
	v_and_b32_e32 v5, 32, v5
	v_bfe_i32 v11, v1, 0, 16
	v_add_lshl_u32 v1, v5, v11, 1
	v_lshl_add_u32 v130, v4, 12, v1
	v_lshl_add_u32 v132, v3, 12, v1
	v_bfe_i32 v1, v9, 27, 1
	v_lshrrev_b32_e32 v1, 22, v1
	v_add_u32_e32 v1, v0, v1
	v_and_b32_e32 v1, 0xfffffc00, v1
	v_sub_u32_e32 v0, v0, v1
	v_lshrrev_b32_e32 v1, 4, v0
	v_ashrrev_i32_e32 v3, 31, v9
	v_bitop3_b32 v0, v1, v0, 32 bitop3:0x6c
	v_lshrrev_b32_e32 v3, 26, v3
	v_ashrrev_i32_e32 v1, 31, v0
	v_add_u32_e32 v3, v9, v3
	v_lshrrev_b32_e32 v1, 26, v1
	v_ashrrev_i32_e32 v13, 6, v3
	v_readlane_b32 s0, v254, 14
	v_add_u32_e32 v1, v0, v1
	v_lshlrev_b32_e32 v3, 3, v13
	v_readlane_b32 s1, v254, 15
	s_add_u32 s0, s0, 0x3800000
	v_ashrrev_i32_e32 v12, 6, v1
	v_and_b32_e32 v3, -16, v3
	s_addc_u32 s1, s1, 0
	v_add_u32_e32 v3, v12, v3
	v_and_b32_e32 v4, 3, v12
	s_ashr_i32 s36, s2, 31
	v_and_or_b32 v4, v3, s8, v4
	s_lshr_b32 s8, s36, 29
	s_add_i32 s8, s2, s8
	s_ashr_i32 s6, s7, 6
	s_ashr_i32 s10, s8, 3
	s_and_b32 s8, s8, -8
	s_ashr_i32 s9, s7, 8
	s_lshl_b32 s3, s6, 10
	s_sub_i32 s8, s2, s8
	s_cmp_lt_i32 s8, 0
	s_movk_i32 s37, 0x161
	s_cselect_b32 s11, s37, 0x160
	s_mul_i32 s8, s8, s11
	s_add_i32 s8, s8, s10
	s_mul_hi_i32 s10, s8, 0x2e8ba2e9
	s_lshr_b32 s11, s10, 31
	s_ashr_i32 s10, s10, 6
	s_add_i32 s10, s10, s11
	s_lshl_b32 s11, s10, 3
	s_mulk_i32 s10, 0x160
	s_sub_i32 s10, s8, s10
	s_sext_i32_i16 s8, s10
	s_bfe_u32 s8, s8, 0x3001c
	s_add_i32 s12, s10, s8
	s_sext_i32_i16 s8, s12
	s_and_b32 s12, s12, 0xfff8
	s_sub_i32 s10, s10, s12
	s_sext_i32_i16 s10, s10
	v_lshrrev_b32_e32 v5, 2, v3
	v_lshlrev_b32_e32 v6, 1, v3
	v_and_b32_e32 v1, 0xc0, v1
	s_lshr_b32 s8, s8, 3
	s_sub_i32 s8, 43, s8
	s_add_i32 s28, s11, s10
	v_and_b32_e32 v5, 4, v5
	v_and_b32_e32 v6, 24, v6
	v_sub_u32_e32 v0, v0, v1
	s_ashr_i32 s29, s28, 31
	s_bfe_i64 s[12:13], s[8:9], 0x100000
	v_or3_b32 v4, v4, v5, v6
	v_lshlrev_b32_e32 v5, 5, v13
	v_ashrrev_i16_sdwa v0, v2, sext(v0) dst_sel:DWORD dst_unused:UNUSED_PAD src0_sel:DWORD src1_sel:BYTE_0
	s_lshl_b64 s[10:11], s[28:29], 20
	s_lshl_b64 s[12:13], s[12:13], 20
	v_and_b32_e32 v5, 32, v5
	v_bfe_i32 v14, v0, 0, 16
	s_add_u32 s42, s0, s12
	v_add_lshl_u32 v0, v5, v14, 1
	s_addc_u32 s43, s1, s13
	s_add_i32 s29, s3, 0
	v_lshl_add_u32 v134, v4, 12, v0
	s_add_i32 m0, s29, 0x10000
	v_lshl_add_u32 v136, v3, 12, v0
	global_load_lds_dwordx4 v134, s[42:43]
	s_add_i32 m0, s29, 0x12000
	s_add_u32 s12, s42, 0x80000
	global_load_lds_dwordx4 v130, s[42:43]
	s_addc_u32 s13, s43, 0
	s_add_i32 m0, s29, 0x14000
	v_mov_b32_e32 v135, 0
	global_load_lds_dwordx4 v134, s[12:13]
	s_add_i32 m0, s29, 0x16000
	s_add_u32 s30, s40, s10
	s_addc_u32 s31, s41, s11
	s_add_i32 s38, s29, 0x2000
	global_load_lds_dwordx4 v130, s[12:13]
	s_mov_b32 m0, s29
	s_add_u32 s10, s30, 0x80000
	global_load_lds_dwordx4 v136, s[30:31]
	s_mov_b32 m0, s38
	s_addc_u32 s11, s31, 0
	s_add_i32 s39, s29, 0x4000
	global_load_lds_dwordx4 v132, s[30:31]
	s_mov_b32 m0, s39
	s_add_i32 s46, s29, 0x6000
	global_load_lds_dwordx4 v136, s[10:11]
	s_mov_b32 m0, s46
	v_mov_b32_e32 v131, v135
	global_load_lds_dwordx4 v132, s[10:11]
	v_mov_b32_e32 v137, v135
	v_mov_b32_e32 v133, v135
	s_cmp_eq_u32 s9, 1
	s_mov_b32 s47, 0
	v_lshl_add_u64 v[6:7], s[42:43], 0, v[134:135]
	v_lshl_add_u64 v[4:5], s[42:43], 0, v[130:131]
	v_lshl_add_u64 v[0:1], s[30:31], 0, v[136:137]
	s_cselect_b64 s[10:11], -1, 0
	s_cmp_lg_u32 s9, 1
	v_lshl_add_u64 v[2:3], s[30:31], 0, v[132:133]
	s_cbranch_scc1 .LBB0_1481
	s_barrier

.LBB0_1484:
	s_add_i32 s47, s47, 1
	s_mul_i32 s7, s47, s50
	s_mul_hi_u32 s8, s47, s51
	s_add_i32 s8, s8, s7
	s_mul_i32 s7, s47, s51
	s_add_u32 s22, s7, s2
	s_addc_u32 s23, s8, s36
	v_cmp_gt_i64_e32 vcc, s[22:23], v[144:145]
	v_cmp_lt_i64_e64 s[8:9], s[22:23], v[142:143]
	s_cbranch_vccnz .LBB0_1486
	s_ashr_i32 s7, s22, 31
	s_lshr_b32 s7, s7, 29
	s_add_i32 s7, s22, s7
	s_ashr_i32 s14, s7, 3
	s_and_b32 s7, s7, -8
	s_sub_i32 s7, s22, s7
	s_cmp_lt_i32 s7, 0
	s_cselect_b32 s15, s37, 0x160
	s_mul_i32 s7, s7, s15
	s_add_i32 s7, s7, s14
	s_mul_hi_i32 s14, s7, 0x2e8ba2e9
	s_lshr_b32 s15, s14, 31
	s_ashr_i32 s14, s14, 6
	s_add_i32 s14, s14, s15
	s_lshl_b32 s15, s14, 3
	s_sub_i32 s18, 64, s15
	s_min_i32 s19, s18, 8
	s_abs_i32 s18, s19
	v_cvt_f32_u32_e32 v0, s18
	s_sub_i32 s21, 0, s18
	s_mulk_i32 s14, 0x160
	s_sub_i32 s7, s7, s14
	v_rcp_iflag_f32_e32 v0, v0
	s_abs_i32 s14, s7
	s_xor_b32 s20, s7, s19
	s_ashr_i32 s20, s20, 31
	v_mul_f32_e32 v0, 0x4f7ffffe, v0
	v_cvt_u32_f32_e32 v0, v0
	s_nop 0
	v_readfirstlane_b32 s22, v0
	s_mul_i32 s21, s21, s22
	s_mul_hi_u32 s21, s22, s21
	s_add_i32 s22, s22, s21
	s_mul_hi_u32 s21, s14, s22
	s_mul_i32 s22, s21, s18
	s_sub_i32 s14, s14, s22
	s_add_i32 s23, s21, 1
	s_sub_i32 s22, s14, s18
	s_cmp_ge_u32 s14, s18
	s_cselect_b32 s21, s23, s21
	s_cselect_b32 s14, s22, s14
	s_add_i32 s22, s21, 1
	s_cmp_ge_u32 s14, s18
	s_cselect_b32 s14, s22, s21
	s_xor_b32 s14, s14, s20
	s_sub_i32 s18, s14, s20
	s_mul_i32 s14, s18, s19
	s_sub_i32 s7, s7, s14
	s_add_i32 s20, s15, s7
	s_sub_i32 s18, 43, s18
